# stagger: workgroups with slack start the multi-round GEMM phases late (P1: WGs 192-255 by 2x s_sleep 127, P9: WGs 128-255 by 3x) so the chip-wide epilogue store bursts of the two groups no longer coin
# speedup vs baseline: 1.0056x; 1.0023x over previous
.LBB0_182:
	s_or_b64 exec, exec, s[8:9]
	s_waitcnt lgkmcnt(0)
	s_barrier
	s_cmp_lt_u32 s2, 0xc0
	s_cbranch_scc1 stag_skip_0
	s_sleep 127
	s_sleep 127
stag_skip_0:
.LBB0_183:
	s_cmp_lt_i32 s92, 2
	s_cselect_b64 s[96:97], -1, 0
	s_add_u32 s20, s30, 0x6000000
	s_addc_u32 s21, s31, 0
	s_and_b64 s[0:1], s[96:97], s[0:1]
	s_mov_b64 s[80:81], s[72:73]
	s_andn2_b64 vcc, exec, s[0:1]
	s_cbranch_vccnz .LBB0_385
	s_waitcnt vmcnt(0)
	v_lshlrev_b32_e32 v1, 4, v223
	v_and_b32_e32 v0, 32, v223
	v_bitop3_b32 v174, v1, v0, 48 bitop3:0x6c
	v_lshrrev_b32_e32 v0, 1, v223
	v_lshrrev_b32_e32 v3, 5, v223
	v_and_b32_e32 v0, 24, v0
	v_and_b32_e32 v3, 4, v3
	v_bfe_u32 v4, v223, 2, 2
	v_bfe_u32 v176, v223, 2, 4
	v_or3_b32 v3, v3, v4, v0
	v_lshrrev_b32_e32 v4, 3, v223
	s_movk_i32 s0, 0x70
	v_and_b32_e32 v175, 64, v223
	v_and_or_b32 v5, v4, s0, v176
	s_movk_i32 s0, 0x60
	v_add_u32_e32 v177, 0x2000, v1
	v_or_b32_e32 v2, v174, v175
	v_and_or_b32 v4, v4, s0, v3
	v_lshrrev_b32_e32 v1, 7, v177
	s_movk_i32 s0, 0xf0
	s_add_u32 s10, s30, 0x200000
	v_lshl_or_b32 v148, v4, 11, v2
	v_and_or_b32 v4, v1, s0, v176
	s_movk_i32 s0, 0xe0
	s_addc_u32 s11, s31, 0
	v_and_or_b32 v1, v1, s0, v3
	v_lshlrev_b32_e32 v144, 6, v223
	v_lshlrev_b32_e32 v145, 2, v223
	v_readfirstlane_b32 s9, v223
	v_lshl_or_b32 v146, v5, 11, v2
	v_lshl_or_b32 v150, v4, 11, v2
	v_lshl_or_b32 v152, v1, 11, v2
	v_and_b32_e32 v179, 15, v223
	v_and_b32_e32 v178, 0x3c0, v144
	s_cmpk_gt_i32 s2, 0x37f
	v_and_b32_e32 v180, 32, v145
	s_cbranch_scc1 .LBB0_208
	s_ashr_i32 s17, s2, 31
	s_lshr_b32 s0, s17, 29
	s_add_i32 s0, s2, s0
	s_lshr_b32 s12, s9, 6
	s_ashr_i32 s1, s0, 3
	s_and_b32 s0, s0, -8
	s_lshr_b32 s14, s9, 8
	s_lshl_b32 s3, s12, 10
	s_sub_i32 s0, s2, s0
	s_cmp_lt_i32 s0, 0
	s_movk_i32 s8, 0x71
	s_cselect_b32 s8, s8, 0x70
	s_mul_i32 s0, s0, s8
	s_add_i32 s0, s0, s1
	s_mul_hi_i32 s1, s0, 0x92492493
	s_add_i32 s1, s1, s0
	s_lshr_b32 s8, s1, 31
	s_ashr_i32 s1, s1, 6
	s_add_i32 s1, s1, s8
	s_lshl_b32 s13, s1, 3
	s_mulk_i32 s1, 0x70
	s_sub_i32 s0, s0, s1
	s_bfe_i32 s1, s0, 0x80000
	s_bfe_u32 s1, s1, 0x3000c
	s_add_i32 s1, s0, s1
	s_bfe_i32 s8, s1, 0x80000
	s_and_b32 s1, s1, 0xf8
	s_sub_i32 s0, s0, s1
	s_sext_i32_i16 s8, s8
	s_sext_i32_i8 s0, s0
	s_lshr_b32 s8, s8, 3
	s_add_i32 s78, s13, s0
	s_ashr_i32 s79, s78, 31
	s_bfe_i64 s[18:19], s[8:9], 0x100000
	s_lshl_b64 s[0:1], s[78:79], 19
	s_lshl_b64 s[18:19], s[18:19], 19
	s_add_u32 s70, s10, s18
	s_addc_u32 s71, s11, s19
	s_add_i32 s27, s3, 0
	s_add_i32 m0, s27, 0x10000
	v_mov_b32_e32 v155, 0
	global_load_lds_dwordx4 v148, s[70:71]
	s_add_i32 m0, s27, 0x12000
	s_add_u32 s18, s70, 0x40000
	global_load_lds_dwordx4 v152, s[70:71]
	s_addc_u32 s19, s71, 0
	s_add_i32 m0, s27, 0x14000
	v_mov_b32_e32 v149, v155
	global_load_lds_dwordx4 v148, s[18:19]
	s_add_i32 m0, s27, 0x16000
	s_add_u32 s68, s24, s0
	s_addc_u32 s69, s25, s1
	s_add_i32 s35, s27, 0x2000
	global_load_lds_dwordx4 v152, s[18:19]
	s_mov_b32 m0, s27
	s_add_u32 s0, s68, 0x40000
	global_load_lds_dwordx4 v146, s[68:69]
	s_mov_b32 m0, s35
	s_addc_u32 s1, s69, 0
	s_add_i32 s74, s27, 0x4000
	global_load_lds_dwordx4 v150, s[68:69]
	s_mov_b32 m0, s74
	s_add_i32 s75, s27, 0x6000
	global_load_lds_dwordx4 v146, s[0:1]
	s_mov_b32 m0, s75
	v_mov_b32_e32 v153, v155
	global_load_lds_dwordx4 v150, s[0:1]
	v_mov_b32_e32 v147, v155
	v_mov_b32_e32 v151, v155
	s_cmp_eq_u32 s14, 1
	s_mov_b32 s79, 0
	v_lshl_add_u64 v[8:9], s[70:71], 0, v[148:149]
	v_lshl_add_u64 v[6:7], s[70:71], 0, v[152:153]
	v_lshl_add_u64 v[2:3], s[68:69], 0, v[146:147]
	s_cselect_b64 s[0:1], -1, 0
	s_cmp_lg_u32 s14, 1
	v_lshl_add_u64 v[4:5], s[68:69], 0, v[150:151]
	s_cbranch_scc1 .LBB0_187
	s_barrier

.LBB0_912:
	s_or_b64 exec, exec, s[4:5]
	s_waitcnt lgkmcnt(0)
	s_barrier
	s_cmp_lt_u32 s2, 0x80
	s_cbranch_scc1 stag_skip_6
	s_sleep 127
	s_sleep 127
	s_sleep 127
stag_skip_6:
.LBB0_913:
	s_cmp_lt_i32 s92, 10
	s_cselect_b64 s[8:9], -1, 0
	s_and_b64 s[0:1], s[8:9], s[0:1]
	s_andn2_b64 vcc, exec, s[0:1]
	s_cbranch_vccnz .LBB0_997
	s_ashr_i32 s3, s2, 31
	s_cmpk_lt_i32 s2, 0x580
	s_cselect_b64 s[4:5], -1, 0
	s_cmpk_gt_i32 s2, 0x57f
	s_cbranch_scc1 .LBB0_923
	s_lshr_b32 s0, s3, 29
	s_add_i32 s0, s2, s0
	s_ashr_i32 s6, s0, 3
	s_and_b32 s0, s0, -8
	s_sub_i32 s0, s2, s0
	s_cmp_lt_i32 s0, 0
	s_movk_i32 s1, 0xb1
	s_cselect_b32 s7, s1, 0xb0
	s_mul_i32 s0, s0, s7
	s_add_i32 s0, s0, s6
	s_mul_hi_i32 s6, s0, 0x2e8ba2e9
	s_lshr_b32 s7, s6, 31
	s_ashr_i32 s6, s6, 5
	s_add_i32 s6, s6, s7
	s_lshl_b32 s7, s6, 3
	s_mulk_i32 s6, 0xb0
	s_sub_i32 s0, s0, s6
	s_bfe_u32 s6, s0, 0x3001c
	s_add_i32 s6, s0, s6
	s_and_b32 s6, s6, 0xfff8
	s_sub_i32 s0, s0, s6
	s_sext_i32_i16 s0, s0
	s_add_i32 s0, s7, s0
	s_ashr_i32 s14, s26, 31
	s_add_u32 s6, s2, s26
	s_addc_u32 s7, s3, s14
	s_waitcnt vmcnt(0) lgkmcnt(0)
	v_mov_b64_e32 v[0:1], 0x57f
	s_branch .LBB0_917
